# v138 + attention weight epilogue dependency spacing (all carry*suffix products first, then e*t products)
# speedup vs baseline: 1.0047x; 1.0047x over previous
; #define LAS __attribute__((address_space(3)))
; __device__ __forceinline__ void attn_unit(LAS unsigned char* lds, const bf16_t* Qm, const bf16_t* Km, const bf16_t* VT, const bf16_t* GBm, bf16_t* YB, int b, int hp, int qb) {
;     ...
;         if (k0 < qw + 15 && !__all(Rs == 0.f)) {
;             f32x4 s[4];
; #pragma unroll
;             for (int rb = 0; rb < 4; ++rb) {
;                 const int c = rb >> 1, e = rb & 1;
;                 const int kl = 32 * c + (fr >> 2) * 8 + e * 4 + (fr & 3);
;                 s[rb] = (f32x4){0.f, 0.f, 0.f, 0.f};
; #pragma unroll
;                 for (int ks = 0; ks < 4; ++ks) {
;                     const bf16x8 a = *(const LAS bf16x8*)(KL + kl * 272 + (ks * 32 + fq * 8) * 2);
;                     s[rb] = __builtin_amdgcn_mfma_f32_16x16x32_bf16(a, qf[ks], s[rb], 0, 0, 0);
;                 }
;             }
;             const int qi = qw + fr;
;             float be[2][8], om[2][8];
; #pragma unroll
;             for (int c = 0; c < 2; ++c)
; #pragma unroll
;                 for (int i = 0; i < 8; ++i) {
;                     const float z = s[2 * c + (i >> 2)][i & 3];
;                     const int key = k0 + 32 * c + 8 * fq + i;
;                     const float e = __builtin_amdgcn_exp2f(-fabsf(z));
;                     const float r = __builtin_amdgcn_rcpf(1.0f + e);
;                     const bool pos = z >= 0.f, valid = key < qi;
;                     be[c][i] = valid ? (pos ? r : e * r) : 0.f;
;                     om[c][i] = valid ? (pos ? e * r : r) : 1.f;
;                 }
;             float suf[2][8], Gs[2], Tt[2];
; #pragma unroll
;             for (int c = 0; c < 2; ++c) {
;                 float run = 1.f;
; #pragma unroll
;                 for (int i = 7; i >= 0; --i) { suf[c][i] = run; run *= om[c][i]; }
;                 const float t1 = __shfl(run, (lane + 16) & 63), t2 = __shfl(run, (lane + 32) & 63), t3 = __shfl(run, (lane + 48) & 63);
;                 Gs[c] = (fq < 3 ? t1 : 1.f) * (fq < 2 ? t2 : 1.f) * (fq < 1 ? t3 : 1.f);
;                 Tt[c] = (run * t1) * (t2 * t3);
;             }
.Lattn_nomask:
	ds_read_b128 v[120:123], v116
	ds_read_b128 v[124:127], v116 offset:64
	ds_read_b128 v[128:131], v116 offset:1088
	ds_read_b128 v[132:135], v116 offset:1152
	s_waitcnt lgkmcnt(3)
	v_mfma_f32_16x16x32_bf16 v[120:123], v[120:123], v[0:3], 0
	s_waitcnt lgkmcnt(2)
	v_mfma_f32_16x16x32_bf16 v[120:123], v[124:127], v[4:7], v[120:123]
	ds_read_b128 v[124:127], v116 offset:128
	ds_read_b128 v[136:139], v116 offset:192
	s_waitcnt lgkmcnt(3)
	v_mfma_f32_16x16x32_bf16 v[128:131], v[128:131], v[0:3], 0
	s_waitcnt lgkmcnt(1)
	v_mfma_f32_16x16x32_bf16 v[120:123], v[124:127], v[8:11], v[120:123]
	ds_read_b128 v[124:127], v116 offset:1216
	ds_read_b128 v[140:143], v116 offset:1280
	ds_read_b128 v[144:147], v116 offset:8704
	ds_read_b128 v[148:151], v116 offset:8768
	v_mfma_f32_16x16x32_bf16 v[128:131], v[132:135], v[4:7], v[128:131]
	ds_read_b128 v[132:135], v116 offset:8832
	ds_read_b128 v[152:155], v116 offset:8896
	ds_read_b128 v[156:159], v116 offset:9792
	ds_read_b128 v[160:163], v116 offset:9856
	s_waitcnt lgkmcnt(8)
	v_mfma_f32_16x16x32_bf16 v[120:123], v[136:139], v[12:15], v[120:123]
	ds_read_b128 v[136:139], v116 offset:9920
	ds_read_b128 v[164:167], v116 offset:9984
	s_waitcnt lgkmcnt(9)
	v_mfma_f32_16x16x32_bf16 v[124:127], v[124:127], v[8:11], v[128:131]
	s_nop 3
	v_exp_f32_e32 v97, v120
	s_nop 0
	v_add_f32_e32 v101, 1.0, v97
	s_waitcnt lgkmcnt(7)
	v_mfma_f32_16x16x32_bf16 v[128:131], v[144:147], v[0:3], 0
	v_rcp_f32_e32 v168, v101
	s_nop 0
	v_mul_f32_e32 v101, v97, v168
	s_waitcnt lgkmcnt(6)
	v_mfma_f32_16x16x32_bf16 v[128:131], v[148:151], v[4:7], v[128:131]
	v_mfma_f32_16x16x32_bf16 v[124:127], v[140:143], v[12:15], v[124:127]
	v_exp_f32_e32 v142, v121
	v_exp_f32_e32 v143, v122
	s_waitcnt lgkmcnt(5)
	v_mfma_f32_16x16x32_bf16 v[128:131], v[132:135], v[8:11], v[128:131]
	v_add_f32_e32 v103, 1.0, v142
	v_rcp_f32_e32 v103, v103
	s_waitcnt lgkmcnt(3)
	v_mfma_f32_16x16x32_bf16 v[132:135], v[156:159], v[0:3], 0
	v_add_f32_e32 v120, 1.0, v143
	v_rcp_f32_e32 v120, v120
	s_waitcnt lgkmcnt(2)
	v_mfma_f32_16x16x32_bf16 v[132:135], v[160:163], v[4:7], v[132:135]
	s_waitcnt lgkmcnt(1)
	v_mfma_f32_16x16x32_bf16 v[132:135], v[136:139], v[8:11], v[132:135]
	v_exp_f32_e32 v144, v123
	v_exp_f32_e32 v145, v124
	v_add_f32_e32 v121, 1.0, v144
	v_rcp_f32_e32 v121, v121
	v_add_f32_e32 v122, 1.0, v145
	v_rcp_f32_e32 v122, v122
	v_mfma_f32_16x16x32_bf16 v[128:131], v[152:155], v[12:15], v[128:131]
	s_nop 0
	s_nop 0
	v_exp_f32_e32 v146, v125
	s_nop 0
	v_add_f32_e32 v123, 1.0, v146
	v_rcp_f32_e32 v123, v123
	s_nop 0
	s_nop 0
	v_exp_f32_e32 v138, v128
	v_exp_f32_e32 v131, v131
	v_exp_f32_e32 v126, v126
	s_nop 0
	v_add_f32_e32 v124, 1.0, v126
	v_rcp_f32_e32 v124, v124
	s_waitcnt lgkmcnt(0)
	v_mfma_f32_16x16x32_bf16 v[132:135], v[164:167], v[12:15], v[132:135]
	v_exp_f32_e32 v127, v127
	s_nop 0
	v_add_f32_e32 v125, 1.0, v127
	v_rcp_f32_e32 v147, v125
	v_add_f32_e32 v136, 1.0, v138
	v_rcp_f32_e32 v140, v136
	v_exp_f32_e32 v129, v129
	v_exp_f32_e32 v130, v130
	v_mul_f32_e32 v128, v138, v140
	v_add_f32_e32 v125, 1.0, v129
	v_add_f32_e32 v136, 1.0, v130
	v_add_f32_e32 v137, 1.0, v131
	v_rcp_f32_e32 v125, v125
	v_rcp_f32_e32 v141, v136
	v_rcp_f32_e32 v148, v137
	v_mul_f32_e32 v153, v147, v124
	v_mul_f32_e32 v154, v123, v153
	v_mul_f32_e32 v155, v122, v154
	v_exp_f32_e32 v132, v132
	v_exp_f32_e32 v133, v133
	v_exp_f32_e32 v134, v134
	v_exp_f32_e32 v99, v135
	v_mul_f32_e32 v156, v121, v155
	v_add_f32_e32 v136, 1.0, v132
	v_add_f32_e32 v137, 1.0, v133
	v_add_f32_e32 v138, 1.0, v134
	v_add_f32_e32 v139, 1.0, v99
	v_rcp_f32_e32 v149, v136
	v_rcp_f32_e32 v150, v137
	v_rcp_f32_e32 v152, v138
	v_rcp_f32_e32 v151, v139
	v_mul_f32_e32 v157, v120, v156
	v_mul_f32_e32 v103, v103, v157
	v_mul_f32_e32 v136, v168, v103
	v_or_b32_e32 v135, v105, v107
	v_lshlrev_b32_e32 v135, 2, v135
	v_xor_b32_e32 v135, 0x80, v135
	v_mul_f32_e32 v152, v151, v152
	ds_bpermute_b32 v137, v135, v136
	ds_bpermute_b32 v138, v118, v136
	v_mul_f32_e32 v150, v150, v152
	v_mul_f32_e32 v149, v149, v150
	v_mul_f32_e32 v148, v148, v149
	v_mul_f32_e32 v158, v141, v148
	v_mul_f32_e32 v159, v125, v158
	ds_bpermute_b32 v139, v119, v136
	s_waitcnt lgkmcnt(2)
	v_cndmask_b32_e64 v97, 1.0, v137, s[10:11]
	s_waitcnt lgkmcnt(1)
; #define LAS __attribute__((address_space(3)))
; __device__ __forceinline__ unsigned cvt_pk_bf16(float lo, float hi) { unsigned r; asm volatile("v_cvt_pk_bf16_f32 %0, %1, %2" : "=v"(r) : "v"(lo), "v"(hi)); return r; }
; __device__ __forceinline__ void attn_unit(LAS unsigned char* lds, const bf16_t* Qm, const bf16_t* Km, const bf16_t* VT, const bf16_t* GBm, bf16_t* YB, int b, int hp, int qb) {
;     ...
;                 const float t1 = __shfl(run, (lane + 16) & 63), t2 = __shfl(run, (lane + 32) & 63), t3 = __shfl(run, (lane + 48) & 63);
;                 Gs[c] = (fq < 3 ? t1 : 1.f) * (fq < 2 ? t2 : 1.f) * (fq < 1 ? t3 : 1.f);
;                 Tt[c] = (run * t1) * (t2 * t3);
;             }
;             bf16x8 pf[2];
; #pragma unroll
;             for (int c = 0; c < 2; ++c) {
;                 const float basec = Rs * Gs[c] * (c == 0 ? Tt[1] : 1.f);
;                 float w[8];
; #pragma unroll
;                 for (int i = 0; i < 8; ++i) w[i] = be[c][i] * (suf[c][i] * basec);
;                 u32x4 pw; pw.x = cvt_pk_bf16(w[0], w[1]); pw.y = cvt_pk_bf16(w[2], w[3]); pw.z = cvt_pk_bf16(w[4], w[5]); pw.w = cvt_pk_bf16(w[6], w[7]);
;                 pf[c] = __builtin_bit_cast(bf16x8, pw);
;             }
;             Rs *= Tt[0] * Tt[1];
; #pragma unroll
;             for (int db = 0; db < 8; ++db)
; #pragma unroll
;                 for (int c = 0; c < 2; ++c) {
;                     const bf16x8 a = *(const LAS bf16x8*)(VL + (db * 16 + fr) * 144 + (32 * c + 8 * fq) * 2);
;                     o[db] = __builtin_amdgcn_mfma_f32_16x16x32_bf16(a, pf[c], o[db], 0, 0, 0);
;                 }
	v_cndmask_b32_e64 v120, v138, 1.0, s[0:1]
	v_mul_f32_e32 v121, v140, v159
	v_mul_f32_e32 v97, v120, v97
	ds_bpermute_b32 v120, v135, v121
	ds_bpermute_b32 v123, v118, v121
	ds_bpermute_b32 v122, v119, v121
	s_waitcnt lgkmcnt(3)
	v_cndmask_b32_e64 v124, 1.0, v139, s[4:5]
	v_mul_f32_e32 v124, v97, v124
	s_waitcnt lgkmcnt(2)
	v_cndmask_b32_e64 v97, 1.0, v120, s[10:11]
	s_waitcnt lgkmcnt(1)
	v_cndmask_b32_e64 v125, v123, 1.0, s[0:1]
	v_mul_f32_e32 v97, v125, v97
	s_waitcnt lgkmcnt(0)
	v_cndmask_b32_e64 v125, 1.0, v122, s[4:5]
	v_mul_f32_e32 v120, v120, v122
	v_mul_f32_e32 v121, v121, v123
	v_mul_f32_e32 v135, v97, v125
	v_mul_f32_e32 v140, v96, v124
	v_mul_f32_e32 v141, v120, v121
	v_mul_f32_e32 v97, v140, v141
	v_mul_f32_e32 v228, v103, v97
	v_mul_f32_e32 v229, v157, v97
	v_mul_f32_e32 v230, v156, v97
	v_mul_f32_e32 v231, v155, v97
	v_mul_f32_e32 v232, v154, v97
	v_mul_f32_e32 v233, v153, v97
	v_mul_f32_e32 v234, v147, v97
	v_mul_f32_e32 v101, v101, v228
	v_mul_f32_e32 v103, v142, v228
	v_mul_f32_e32 v121, v143, v229
	v_mul_f32_e32 v122, v144, v230
	v_mul_f32_e32 v123, v145, v231
	v_mul_f32_e32 v124, v146, v232
	v_mul_f32_e32 v125, v126, v233
	v_mul_f32_e32 v97, v127, v234
	v_cvt_pk_bf16_f32 v120, v101, v103
	v_cvt_pk_bf16_f32 v121, v121, v122
	v_cvt_pk_bf16_f32 v122, v123, v124
	v_cvt_pk_bf16_f32 v123, v125, v97
	v_mul_f32_e32 v97, v96, v135
	v_mul_f32_e32 v228, v97, v159
	v_mul_f32_e32 v229, v97, v158
	v_mul_f32_e32 v230, v97, v148
	v_mul_f32_e32 v231, v97, v149
	v_mul_f32_e32 v232, v97, v150
	v_mul_f32_e32 v233, v97, v152
	v_mul_f32_e32 v234, v151, v97
	v_mul_f32_e32 v101, v128, v228
	v_mul_f32_e32 v103, v129, v228
	v_mul_f32_e32 v125, v130, v229
	v_mul_f32_e32 v126, v131, v230
	v_mul_f32_e32 v127, v132, v231
	v_mul_f32_e32 v128, v133, v232
	v_mul_f32_e32 v129, v134, v233
	v_mul_f32_e32 v97, v99, v234
	v_cvt_pk_bf16_f32 v124, v101, v103
	v_cvt_pk_bf16_f32 v125, v125, v126
	v_cvt_pk_bf16_f32 v126, v127, v128
	v_cvt_pk_bf16_f32 v127, v129, v97
	ds_read_b128 v[128:131], v117 offset:17408
	ds_read_b128 v[132:135], v117 offset:17472
	s_waitcnt lgkmcnt(1)
	v_mfma_f32_16x16x32_bf16 v[60:63], v[128:131], v[120:123], v[60:63]
	ds_read_b128 v[128:131], v117 offset:19712
	s_waitcnt lgkmcnt(1)
	v_mfma_f32_16x16x32_bf16 v[60:63], v[132:135], v[124:127], v[60:63]
	ds_read_b128 v[132:135], v117 offset:19776
	s_waitcnt lgkmcnt(1)
	v_mfma_f32_16x16x32_bf16 v[72:75], v[128:131], v[120:123], v[72:75]
	ds_read_b128 v[128:131], v117 offset:22016
	s_waitcnt lgkmcnt(1)
	v_mfma_f32_16x16x32_bf16 v[72:75], v[132:135], v[124:127], v[72:75]
	ds_read_b128 v[132:135], v117 offset:22080
	s_waitcnt lgkmcnt(1)
	v_mfma_f32_16x16x32_bf16 v[56:59], v[128:131], v[120:123], v[56:59]
	ds_read_b128 v[128:131], v117 offset:24320
	s_waitcnt lgkmcnt(1)
	v_mfma_f32_16x16x32_bf16 v[56:59], v[132:135], v[124:127], v[56:59]
	ds_read_b128 v[132:135], v117 offset:24384
	s_waitcnt lgkmcnt(1)
	v_mfma_f32_16x16x32_bf16 v[44:47], v[128:131], v[120:123], v[44:47]
	ds_read_b128 v[128:131], v117 offset:26624
	s_waitcnt lgkmcnt(1)
	v_mfma_f32_16x16x32_bf16 v[44:47], v[132:135], v[124:127], v[44:47]
	ds_read_b128 v[132:135], v117 offset:26688
	s_waitcnt lgkmcnt(1)
	v_mfma_f32_16x16x32_bf16 v[32:35], v[128:131], v[120:123], v[32:35]
	ds_read_b128 v[128:131], v117 offset:28928
	s_waitcnt lgkmcnt(1)
	v_mfma_f32_16x16x32_bf16 v[32:35], v[132:135], v[124:127], v[32:35]
	ds_read_b128 v[132:135], v117 offset:28992
	s_waitcnt lgkmcnt(1)
	v_mfma_f32_16x16x32_bf16 v[24:27], v[128:131], v[120:123], v[24:27]
	ds_read_b128 v[128:131], v117 offset:31232
	s_waitcnt lgkmcnt(1)
	v_mfma_f32_16x16x32_bf16 v[24:27], v[132:135], v[124:127], v[24:27]
	ds_read_b128 v[132:135], v117 offset:31296
	s_waitcnt lgkmcnt(1)
	v_mfma_f32_16x16x32_bf16 v[20:23], v[128:131], v[120:123], v[20:23]
	ds_read_b128 v[128:131], v117 offset:33536
	s_waitcnt lgkmcnt(1)
	v_mfma_f32_16x16x32_bf16 v[20:23], v[132:135], v[124:127], v[20:23]
	ds_read_b128 v[132:135], v117 offset:33600
	s_waitcnt lgkmcnt(1)
	v_mfma_f32_16x16x32_bf16 v[16:19], v[128:131], v[120:123], v[16:19]
	v_mul_f32_e64 v120, v136, v138
	v_mul_f32_e64 v121, v137, v139
	v_mul_f32_e32 v97, v120, v121
	s_waitcnt lgkmcnt(0)
	v_mfma_f32_16x16x32_bf16 v[16:19], v[132:135], v[124:127], v[16:19]
	v_mul_f32_e32 v97, v97, v141
	v_mul_f32_e32 v96, v96, v97
